# grid barrier spin loops: 3 polls kept in flight (pipelined sc1 flag loads) instead of one load per round trip
# baseline (speedup 1.0000x reference)
.LBB0_515:
	global_load_dword v0, v175, s[28:29] sc1
	s_sleep 12
	global_load_dword v14, v175, s[28:29] sc1
	s_sleep 12
	global_load_dword v15, v175, s[28:29] sc1
.Lxbspin1:
	s_waitcnt vmcnt(2)
	v_cmp_ne_u32_e32 vcc, v0, v1
	s_cbranch_vccnz .Lxbdone1
	global_load_dword v0, v175, s[28:29] sc1
	s_waitcnt vmcnt(2)
	v_cmp_ne_u32_e32 vcc, v14, v1
	s_cbranch_vccnz .Lxbdone1
	global_load_dword v14, v175, s[28:29] sc1
	s_waitcnt vmcnt(2)
	v_cmp_ne_u32_e32 vcc, v15, v1
	s_cbranch_vccnz .Lxbdone1
	global_load_dword v15, v175, s[28:29] sc1
	s_branch .Lxbspin1
.Lxbdone1:
	s_add_i32 s4, s4, 1
	s_mov_b64 s[40:41], -1
	s_waitcnt vmcnt(0)
	s_orn2_b64 s[38:39], vcc, exec
	s_branch .LBB0_510

.LBB0_532:
	global_load_dword v0, v175, s[10:11] sc1
	s_sleep 12
	global_load_dword v14, v175, s[10:11] sc1
	s_sleep 12
	global_load_dword v15, v175, s[10:11] sc1
.Lxbspin2:
	s_waitcnt vmcnt(2)
	v_cmp_ne_u32_e32 vcc, v0, v2
	s_cbranch_vccnz .Lxbdone2
	global_load_dword v0, v175, s[10:11] sc1
	s_waitcnt vmcnt(2)
	v_cmp_ne_u32_e32 vcc, v14, v2
	s_cbranch_vccnz .Lxbdone2
	global_load_dword v14, v175, s[10:11] sc1
	s_waitcnt vmcnt(2)
	v_cmp_ne_u32_e32 vcc, v15, v2
	s_cbranch_vccnz .Lxbdone2
	global_load_dword v15, v175, s[10:11] sc1
	s_branch .Lxbspin2
.Lxbdone2:
	s_add_i32 s4, s4, 1
	s_mov_b64 s[38:39], -1
	s_waitcnt vmcnt(0)
	s_orn2_b64 s[34:35], vcc, exec
	s_branch .LBB0_527

.Lxbdone3:
	s_add_i32 s4, s4, 1
	s_mov_b64 s[38:39], -1
	s_waitcnt vmcnt(0)
	s_orn2_b64 s[36:37], vcc, exec
	s_branch .LBB0_800

.Lxbdone4:
	s_add_i32 s4, s4, 1
	s_mov_b64 s[36:37], -1
	s_waitcnt vmcnt(0)
	s_orn2_b64 s[34:35], vcc, exec
	s_branch .LBB0_817

.LBB0_1125:
	global_load_dword v0, v175, s[36:37] sc1
	s_sleep 12
	global_load_dword v14, v175, s[36:37] sc1
	s_sleep 12
	global_load_dword v15, v175, s[36:37] sc1
.Lxbspin7:
	s_waitcnt vmcnt(2)
	v_cmp_ne_u32_e32 vcc, v0, v1
	s_cbranch_vccnz .Lxbdone7
	global_load_dword v0, v175, s[36:37] sc1
	s_waitcnt vmcnt(2)
	v_cmp_ne_u32_e32 vcc, v14, v1
	s_cbranch_vccnz .Lxbdone7
	global_load_dword v14, v175, s[36:37] sc1
	s_waitcnt vmcnt(2)
	v_cmp_ne_u32_e32 vcc, v15, v1
	s_cbranch_vccnz .Lxbdone7
	global_load_dword v15, v175, s[36:37] sc1
	s_branch .Lxbspin7
.Lxbdone7:
	s_add_i32 s4, s4, 1
	s_mov_b64 s[44:45], -1
	s_waitcnt vmcnt(0)
	s_orn2_b64 s[42:43], vcc, exec
	s_branch .LBB0_1120

.Lxbdone8:
	s_add_i32 s4, s4, 1
	s_mov_b64 s[42:43], -1
	s_waitcnt vmcnt(0)
	s_orn2_b64 s[40:41], vcc, exec
	s_branch .LBB0_1137
